# staggered small/big GEMM order, groups split by XCD parity instead of row-panel parity
# baseline (speedup 1.0000x reference)
.Lp4_pre:
	s_mov_b64 s[0:1], s[86:87]
	s_load_dwordx2 s[0:1], s[0:1], 0x118
	v_readfirstlane_b32 s20, v0
	s_waitcnt lgkmcnt(0)
	s_add_u32 s8, s0, 0x10a00000
	s_addc_u32 s9, s1, 0
	s_add_u32 s12, s0, 0x200000
	s_addc_u32 s13, s1, 0
	s_add_u32 s10, s0, 0x12e00000
	s_addc_u32 s11, s1, 0
	s_bitcmp1_b32 s2, 0
	s_cbranch_scc0 .Lp4_noswap
	s_cmp_eq_u32 s98, 0
	s_cbranch_scc1 .LBB0_404

.Lp4_small_end:
	s_bitcmp1_b32 s2, 0
	s_cbranch_scc0 .LBB0_407
	s_cmp_eq_u32 s98, 0
	s_cbranch_scc0 .LBB0_407
	s_mov_b32 s98, 1
	s_branch .Lp4_pre

.LBB0_464:
	s_load_dwordx4 s[12:15], s[10:11], 0x0
	s_waitcnt lgkmcnt(0)
	s_add_u32 s20, s8, 0x12e00000
	s_addc_u32 s21, s9, 0
	s_add_u32 s22, s8, 0xa00000
	s_addc_u32 s23, s9, 0
	s_add_u32 s14, s14, 0xfc000000
	s_addc_u32 s15, s15, -1
	s_add_u32 s16, s8, 0x10a00000
	s_addc_u32 s17, s9, 0
	s_add_u32 s18, s8, 0x100000
	s_addc_u32 s19, s9, 0
	s_andn2_b64 vcc, exec, s[6:7]
	v_lshrrev_b32_e32 v152, 4, v0
	s_bitcmp1_b32 s2, 0
	s_cbranch_scc0 .Lp5_noswap
	s_cmp_eq_u32 s98, 0
	s_cbranch_scc1 .LBB0_500

.LBB0_2743:
	s_waitcnt lgkmcnt(0)
	s_add_u32 s22, s6, 0x2d200000
	s_addc_u32 s23, s7, 0
	s_add_u32 s24, s6, 0x6700000
	s_addc_u32 s25, s7, 0
	s_add_u32 s10, s6, 0x10a00000
	s_addc_u32 s11, s7, 0
	s_add_u32 s16, s6, 0x124000
	s_load_dwordx4 s[12:15], s[8:9], 0x100
	s_addc_u32 s17, s7, 0
	s_add_u32 s18, s6, 0x1e200000
	s_addc_u32 s19, s7, 0
	s_add_u32 s20, s6, 0x136000
	s_addc_u32 s21, s7, 0
	s_andn2_b64 vcc, exec, s[4:5]
	v_lshrrev_b32_e32 v158, 4, v0
	s_bitcmp1_b32 s2, 0
	s_cbranch_scc0 .Lp14_noswap
	s_cmp_eq_u32 s98, 0
	s_cbranch_scc1 .LBB0_2779

.LBB0_2991:
	s_load_dwordx4 s[4:7], s[10:11], 0xe0
	s_waitcnt lgkmcnt(0)
	s_add_u32 s10, s28, 0x1aa000
	s_addc_u32 s11, s29, 0
	s_add_u32 s12, s28, 0x10a00000
	s_addc_u32 s13, s29, 0
	s_add_u32 s26, s28, 0xb000000
	s_addc_u32 s27, s29, 0
	s_add_u32 s14, s28, 0xe600000
	s_addc_u32 s15, s29, 0
	s_add_u32 s16, s28, 0x148000
	s_addc_u32 s17, s29, 0
	s_add_u32 s18, s4, 0x2000
	s_addc_u32 s19, s5, 0
	s_add_u32 s20, s6, 0x2000
	s_addc_u32 s21, s7, 0
	s_add_u32 s22, s28, 0x1ac000
	s_addc_u32 s23, s29, 0
	s_add_u32 s24, s28, 0x1e200000
	s_addc_u32 s25, s29, 0
	s_add_u32 s28, s28, 0x15a000
	s_addc_u32 s29, s29, 0
	s_andn2_b64 vcc, exec, s[8:9]
	v_lshrrev_b32_e32 v167, 4, v0
	v_mov_b32_e32 v200, v1
	s_bitcmp1_b32 s2, 0
	s_cbranch_scc0 .Lp19_noswap
	s_cmp_eq_u32 s98, 0
	s_cbranch_scc1 .LBB0_3027

.Lp19_small_end:
	s_bitcmp1_b32 s2, 0
	s_cbranch_scc0 .LBB0_3030
	s_cmp_eq_u32 s98, 0
	s_cbranch_scc0 .LBB0_3030
	s_mov_b32 s98, 1
	v_mov_b32_e32 v1, v200
	s_branch .Lp19_pre
